# scan: 4-op pk chain (no pk_add) + s_setprio 3 on scan waves
# speedup vs baseline: 1.0576x; 1.0148x over previous
.LBB0_850:
	s_barrier
	s_and_saveexec_b64 s[12:13], s[2:3]
	s_xor_b64 s[12:13], exec, s[12:13]
	s_cbranch_execz .LBB0_885
	v_mov_b32_e32 v2, 0
	v_mov_b32_e32 v3, 0
	v_mov_b32_e32 v4, 0
	v_mov_b32_e32 v5, 0
	s_mov_b32 s33, 0
	v_mul_u32_u24_e32 v0, 0x50, v81
	v_and_b32_e32 v98, 63, v200
	s_mov_b32 s30, 0x18000
	v_lshl_add_u32 v98, v98, 2, s30
	v_add_u32_e32 v97, 4, v101
	v_cmp_eq_u32_e64 s[30:31], 8, v81
	v_cndmask_b32_e64 v98, v98, v97, s[4:5]
	s_nop 1
	v_cndmask_b32_e64 v98, v98, v101, s[30:31]
	s_setprio 3
	s_barrier
.Lscan_chunk:
	s_and_b32 s30, s33, 1
	s_mul_i32 s31, s30, 0xa000
	v_add_u32_e32 v94, s31, v0
	s_lshl_b32 s31, s30, 11
	v_add_u32_e32 v95, s31, v100
	v_add_u32_e32 v96, 0x400, v95
	s_lshl_b32 s31, s30, 12
	v_add_u32_e32 v97, s31, v98
	ds_read_b128 v[6:9], v94 offset:0
	ds_read_b128 v[10:13], v94 offset:16
	ds_read_b128 v[14:17], v94 offset:32
	ds_read_b128 v[18:21], v94 offset:48
	ds_read_b128 v[22:25], v94 offset:64
	ds_read2_b32 v[66:67], v95 offset0:0 offset1:16
	ds_read_b128 v[26:29], v94 offset:1280
	ds_read_b128 v[30:33], v94 offset:1296
	ds_read_b128 v[34:37], v94 offset:1312
	ds_read_b128 v[38:41], v94 offset:1328
	ds_read_b128 v[42:45], v94 offset:1344
	s_waitcnt lgkmcnt(5)
	v_pk_mul_f32 v[70:71], v[2:3], v[6:7] op_sel_hi:[0,1]
	v_pk_fma_f32 v[70:71], v[2:3], v[8:9], v[70:71] op_sel:[1,0,0]
	v_pk_fma_f32 v[70:71], v[4:5], v[10:11], v[70:71] op_sel_hi:[0,1,1]
	v_pk_fma_f32 v[70:71], v[4:5], v[12:13], v[70:71] op_sel:[1,0,0]
	v_pk_mul_f32 v[76:77], v[22:23], v[66:67] op_sel_hi:[1,0]
	v_pk_mul_f32 v[92:93], v[24:25], v[66:67] op_sel_hi:[1,0]
	v_add_f32_dpp v74, v71, v70 row_mirror row_mask:0xf bank_mask:0xf bound_ctrl:1
	v_pk_fma_f32 v[76:77], v[2:3], v[14:15], v[76:77]
	v_pk_fma_f32 v[92:93], v[4:5], v[16:17], v[92:93]
	v_add_f32_dpp v74, v74, v74 row_half_mirror row_mask:0xf bank_mask:0xf bound_ctrl:1
	ds_read_b128 v[46:49], v94 offset:2560
	ds_read_b128 v[50:53], v94 offset:2576
	v_add_f32_dpp v74, v74, v74 quad_perm:[1,0,3,2] row_mask:0xf bank_mask:0xf bound_ctrl:1
	ds_read_b128 v[54:57], v94 offset:2592
	ds_read_b128 v[58:61], v94 offset:2608
	v_add_f32_dpp v74, v74, v74 quad_perm:[2,3,0,1] row_mask:0xf bank_mask:0xf bound_ctrl:1
	ds_read_b128 v[62:65], v94 offset:2624
	ds_write_b32 v97, v74 offset:0
	ds_read2_b32 v[68:69], v95 offset0:32 offset1:48
	v_mov_b32_dpp v74, v74 row_mirror row_mask:0xf bank_mask:0xc
	v_pk_fma_f32 v[2:3], v[18:19], v[74:75], v[76:77] op_sel_hi:[1,0,1]
	v_pk_fma_f32 v[4:5], v[20:21], v[74:75], v[92:93] op_sel_hi:[1,0,1]
	s_waitcnt lgkmcnt(7)
	v_pk_mul_f32 v[70:71], v[2:3], v[26:27] op_sel_hi:[0,1]
	v_pk_fma_f32 v[70:71], v[2:3], v[28:29], v[70:71] op_sel:[1,0,0]
	v_pk_fma_f32 v[70:71], v[4:5], v[30:31], v[70:71] op_sel_hi:[0,1,1]
	v_pk_fma_f32 v[70:71], v[4:5], v[32:33], v[70:71] op_sel:[1,0,0]
	v_pk_mul_f32 v[76:77], v[42:43], v[66:67] op_sel:[0,1]
	v_pk_mul_f32 v[92:93], v[44:45], v[66:67] op_sel:[0,1]
	v_add_f32_dpp v74, v71, v70 row_mirror row_mask:0xf bank_mask:0xf bound_ctrl:1
	v_pk_fma_f32 v[76:77], v[2:3], v[34:35], v[76:77]
	v_pk_fma_f32 v[92:93], v[4:5], v[36:37], v[92:93]
	v_add_f32_dpp v74, v74, v74 row_half_mirror row_mask:0xf bank_mask:0xf bound_ctrl:1
	ds_read_b128 v[6:9], v94 offset:3840
	ds_read_b128 v[10:13], v94 offset:3856
	v_add_f32_dpp v74, v74, v74 quad_perm:[1,0,3,2] row_mask:0xf bank_mask:0xf bound_ctrl:1
	ds_read_b128 v[14:17], v94 offset:3872
	ds_read_b128 v[18:21], v94 offset:3888
	v_add_f32_dpp v74, v74, v74 quad_perm:[2,3,0,1] row_mask:0xf bank_mask:0xf bound_ctrl:1
	ds_read_b128 v[22:25], v94 offset:3904
	ds_write_b32 v97, v74 offset:8
	v_mov_b32_dpp v74, v74 row_mirror row_mask:0xf bank_mask:0xc
	v_pk_fma_f32 v[2:3], v[38:39], v[74:75], v[76:77] op_sel_hi:[1,0,1]
	v_pk_fma_f32 v[4:5], v[40:41], v[74:75], v[92:93] op_sel_hi:[1,0,1]
	s_waitcnt lgkmcnt(6)
	v_pk_mul_f32 v[70:71], v[2:3], v[46:47] op_sel_hi:[0,1]
	v_pk_fma_f32 v[70:71], v[2:3], v[48:49], v[70:71] op_sel:[1,0,0]
	v_pk_fma_f32 v[70:71], v[4:5], v[50:51], v[70:71] op_sel_hi:[0,1,1]
	v_pk_fma_f32 v[70:71], v[4:5], v[52:53], v[70:71] op_sel:[1,0,0]
	v_pk_mul_f32 v[76:77], v[62:63], v[68:69] op_sel_hi:[1,0]
	v_pk_mul_f32 v[92:93], v[64:65], v[68:69] op_sel_hi:[1,0]
	v_add_f32_dpp v74, v71, v70 row_mirror row_mask:0xf bank_mask:0xf bound_ctrl:1
	v_pk_fma_f32 v[76:77], v[2:3], v[54:55], v[76:77]
	v_pk_fma_f32 v[92:93], v[4:5], v[56:57], v[92:93]
	v_add_f32_dpp v74, v74, v74 row_half_mirror row_mask:0xf bank_mask:0xf bound_ctrl:1
	ds_read_b128 v[26:29], v94 offset:5120
	ds_read_b128 v[30:33], v94 offset:5136
	v_add_f32_dpp v74, v74, v74 quad_perm:[1,0,3,2] row_mask:0xf bank_mask:0xf bound_ctrl:1
	ds_read_b128 v[34:37], v94 offset:5152
	ds_read_b128 v[38:41], v94 offset:5168
	v_add_f32_dpp v74, v74, v74 quad_perm:[2,3,0,1] row_mask:0xf bank_mask:0xf bound_ctrl:1
	ds_read_b128 v[42:45], v94 offset:5184
	ds_write_b32 v97, v74 offset:256
	ds_read2_b32 v[66:67], v95 offset0:64 offset1:80
	v_mov_b32_dpp v74, v74 row_mirror row_mask:0xf bank_mask:0xc
	v_pk_fma_f32 v[2:3], v[58:59], v[74:75], v[76:77] op_sel_hi:[1,0,1]
	v_pk_fma_f32 v[4:5], v[60:61], v[74:75], v[92:93] op_sel_hi:[1,0,1]
	s_waitcnt lgkmcnt(8)
	v_pk_mul_f32 v[70:71], v[2:3], v[6:7] op_sel_hi:[0,1]
	v_pk_fma_f32 v[70:71], v[2:3], v[8:9], v[70:71] op_sel:[1,0,0]
	v_pk_fma_f32 v[70:71], v[4:5], v[10:11], v[70:71] op_sel_hi:[0,1,1]
	v_pk_fma_f32 v[70:71], v[4:5], v[12:13], v[70:71] op_sel:[1,0,0]
	v_pk_mul_f32 v[76:77], v[22:23], v[68:69] op_sel:[0,1]
	v_pk_mul_f32 v[92:93], v[24:25], v[68:69] op_sel:[0,1]
	v_add_f32_dpp v74, v71, v70 row_mirror row_mask:0xf bank_mask:0xf bound_ctrl:1
	v_pk_fma_f32 v[76:77], v[2:3], v[14:15], v[76:77]
	v_pk_fma_f32 v[92:93], v[4:5], v[16:17], v[92:93]
	v_add_f32_dpp v74, v74, v74 row_half_mirror row_mask:0xf bank_mask:0xf bound_ctrl:1
	ds_read_b128 v[46:49], v94 offset:6400
	ds_read_b128 v[50:53], v94 offset:6416
	v_add_f32_dpp v74, v74, v74 quad_perm:[1,0,3,2] row_mask:0xf bank_mask:0xf bound_ctrl:1
	ds_read_b128 v[54:57], v94 offset:6432
	ds_read_b128 v[58:61], v94 offset:6448
	v_add_f32_dpp v74, v74, v74 quad_perm:[2,3,0,1] row_mask:0xf bank_mask:0xf bound_ctrl:1
	ds_read_b128 v[62:65], v94 offset:6464
	ds_write_b32 v97, v74 offset:264
	v_mov_b32_dpp v74, v74 row_mirror row_mask:0xf bank_mask:0xc
	v_pk_fma_f32 v[2:3], v[18:19], v[74:75], v[76:77] op_sel_hi:[1,0,1]
	v_pk_fma_f32 v[4:5], v[20:21], v[74:75], v[92:93] op_sel_hi:[1,0,1]
	s_waitcnt lgkmcnt(6)
	v_pk_mul_f32 v[70:71], v[2:3], v[26:27] op_sel_hi:[0,1]
	v_pk_fma_f32 v[70:71], v[2:3], v[28:29], v[70:71] op_sel:[1,0,0]
	v_pk_fma_f32 v[70:71], v[4:5], v[30:31], v[70:71] op_sel_hi:[0,1,1]
	v_pk_fma_f32 v[70:71], v[4:5], v[32:33], v[70:71] op_sel:[1,0,0]
	v_pk_mul_f32 v[76:77], v[42:43], v[66:67] op_sel_hi:[1,0]
	v_pk_mul_f32 v[92:93], v[44:45], v[66:67] op_sel_hi:[1,0]
	v_add_f32_dpp v74, v71, v70 row_mirror row_mask:0xf bank_mask:0xf bound_ctrl:1
	v_pk_fma_f32 v[76:77], v[2:3], v[34:35], v[76:77]
	v_pk_fma_f32 v[92:93], v[4:5], v[36:37], v[92:93]
	v_add_f32_dpp v74, v74, v74 row_half_mirror row_mask:0xf bank_mask:0xf bound_ctrl:1
	ds_read_b128 v[6:9], v94 offset:7680
	ds_read_b128 v[10:13], v94 offset:7696
	v_add_f32_dpp v74, v74, v74 quad_perm:[1,0,3,2] row_mask:0xf bank_mask:0xf bound_ctrl:1
	ds_read_b128 v[14:17], v94 offset:7712
	ds_read_b128 v[18:21], v94 offset:7728
	v_add_f32_dpp v74, v74, v74 quad_perm:[2,3,0,1] row_mask:0xf bank_mask:0xf bound_ctrl:1
	ds_read_b128 v[22:25], v94 offset:7744
	ds_write_b32 v97, v74 offset:512
	ds_read2_b32 v[68:69], v95 offset0:96 offset1:112
	v_mov_b32_dpp v74, v74 row_mirror row_mask:0xf bank_mask:0xc
	v_pk_fma_f32 v[2:3], v[38:39], v[74:75], v[76:77] op_sel_hi:[1,0,1]
	v_pk_fma_f32 v[4:5], v[40:41], v[74:75], v[92:93] op_sel_hi:[1,0,1]
	s_waitcnt lgkmcnt(8)
	v_pk_mul_f32 v[70:71], v[2:3], v[46:47] op_sel_hi:[0,1]
	v_pk_fma_f32 v[70:71], v[2:3], v[48:49], v[70:71] op_sel:[1,0,0]
	v_pk_fma_f32 v[70:71], v[4:5], v[50:51], v[70:71] op_sel_hi:[0,1,1]
	v_pk_fma_f32 v[70:71], v[4:5], v[52:53], v[70:71] op_sel:[1,0,0]
	v_pk_mul_f32 v[76:77], v[62:63], v[66:67] op_sel:[0,1]
	v_pk_mul_f32 v[92:93], v[64:65], v[66:67] op_sel:[0,1]
	v_add_f32_dpp v74, v71, v70 row_mirror row_mask:0xf bank_mask:0xf bound_ctrl:1
	v_pk_fma_f32 v[76:77], v[2:3], v[54:55], v[76:77]
	v_pk_fma_f32 v[92:93], v[4:5], v[56:57], v[92:93]
	v_add_f32_dpp v74, v74, v74 row_half_mirror row_mask:0xf bank_mask:0xf bound_ctrl:1
	ds_read_b128 v[26:29], v94 offset:8960
	ds_read_b128 v[30:33], v94 offset:8976
	v_add_f32_dpp v74, v74, v74 quad_perm:[1,0,3,2] row_mask:0xf bank_mask:0xf bound_ctrl:1
	ds_read_b128 v[34:37], v94 offset:8992
	ds_read_b128 v[38:41], v94 offset:9008
	v_add_f32_dpp v74, v74, v74 quad_perm:[2,3,0,1] row_mask:0xf bank_mask:0xf bound_ctrl:1
	ds_read_b128 v[42:45], v94 offset:9024
	ds_write_b32 v97, v74 offset:520
	v_mov_b32_dpp v74, v74 row_mirror row_mask:0xf bank_mask:0xc
	v_pk_fma_f32 v[2:3], v[58:59], v[74:75], v[76:77] op_sel_hi:[1,0,1]
	v_pk_fma_f32 v[4:5], v[60:61], v[74:75], v[92:93] op_sel_hi:[1,0,1]
	s_waitcnt lgkmcnt(6)
	v_pk_mul_f32 v[70:71], v[2:3], v[6:7] op_sel_hi:[0,1]
	v_pk_fma_f32 v[70:71], v[2:3], v[8:9], v[70:71] op_sel:[1,0,0]
	v_pk_fma_f32 v[70:71], v[4:5], v[10:11], v[70:71] op_sel_hi:[0,1,1]
	v_pk_fma_f32 v[70:71], v[4:5], v[12:13], v[70:71] op_sel:[1,0,0]
	v_pk_mul_f32 v[76:77], v[22:23], v[68:69] op_sel_hi:[1,0]
	v_pk_mul_f32 v[92:93], v[24:25], v[68:69] op_sel_hi:[1,0]
	v_add_f32_dpp v74, v71, v70 row_mirror row_mask:0xf bank_mask:0xf bound_ctrl:1
	v_pk_fma_f32 v[76:77], v[2:3], v[14:15], v[76:77]
	v_pk_fma_f32 v[92:93], v[4:5], v[16:17], v[92:93]
	v_add_f32_dpp v74, v74, v74 row_half_mirror row_mask:0xf bank_mask:0xf bound_ctrl:1
	ds_read_b128 v[46:49], v94 offset:10240
	ds_read_b128 v[50:53], v94 offset:10256
	v_add_f32_dpp v74, v74, v74 quad_perm:[1,0,3,2] row_mask:0xf bank_mask:0xf bound_ctrl:1
	ds_read_b128 v[54:57], v94 offset:10272
	ds_read_b128 v[58:61], v94 offset:10288
	v_add_f32_dpp v74, v74, v74 quad_perm:[2,3,0,1] row_mask:0xf bank_mask:0xf bound_ctrl:1
	ds_read_b128 v[62:65], v94 offset:10304
	ds_write_b32 v97, v74 offset:768
	ds_read2_b32 v[66:67], v95 offset0:128 offset1:144
	v_mov_b32_dpp v74, v74 row_mirror row_mask:0xf bank_mask:0xc
	v_pk_fma_f32 v[2:3], v[18:19], v[74:75], v[76:77] op_sel_hi:[1,0,1]
	v_pk_fma_f32 v[4:5], v[20:21], v[74:75], v[92:93] op_sel_hi:[1,0,1]
	s_waitcnt lgkmcnt(8)
	v_pk_mul_f32 v[70:71], v[2:3], v[26:27] op_sel_hi:[0,1]
	v_pk_fma_f32 v[70:71], v[2:3], v[28:29], v[70:71] op_sel:[1,0,0]
	v_pk_fma_f32 v[70:71], v[4:5], v[30:31], v[70:71] op_sel_hi:[0,1,1]
	v_pk_fma_f32 v[70:71], v[4:5], v[32:33], v[70:71] op_sel:[1,0,0]
	v_pk_mul_f32 v[76:77], v[42:43], v[68:69] op_sel:[0,1]
	v_pk_mul_f32 v[92:93], v[44:45], v[68:69] op_sel:[0,1]
	v_add_f32_dpp v74, v71, v70 row_mirror row_mask:0xf bank_mask:0xf bound_ctrl:1
	v_pk_fma_f32 v[76:77], v[2:3], v[34:35], v[76:77]
	v_pk_fma_f32 v[92:93], v[4:5], v[36:37], v[92:93]
	v_add_f32_dpp v74, v74, v74 row_half_mirror row_mask:0xf bank_mask:0xf bound_ctrl:1
	ds_read_b128 v[6:9], v94 offset:11520
	ds_read_b128 v[10:13], v94 offset:11536
	v_add_f32_dpp v74, v74, v74 quad_perm:[1,0,3,2] row_mask:0xf bank_mask:0xf bound_ctrl:1
	ds_read_b128 v[14:17], v94 offset:11552
	ds_read_b128 v[18:21], v94 offset:11568
	v_add_f32_dpp v74, v74, v74 quad_perm:[2,3,0,1] row_mask:0xf bank_mask:0xf bound_ctrl:1
	ds_read_b128 v[22:25], v94 offset:11584
	ds_write_b32 v97, v74 offset:776
	v_mov_b32_dpp v74, v74 row_mirror row_mask:0xf bank_mask:0xc
	v_pk_fma_f32 v[2:3], v[38:39], v[74:75], v[76:77] op_sel_hi:[1,0,1]
	v_pk_fma_f32 v[4:5], v[40:41], v[74:75], v[92:93] op_sel_hi:[1,0,1]
	s_waitcnt lgkmcnt(6)
	v_pk_mul_f32 v[70:71], v[2:3], v[46:47] op_sel_hi:[0,1]
	v_pk_fma_f32 v[70:71], v[2:3], v[48:49], v[70:71] op_sel:[1,0,0]
	v_pk_fma_f32 v[70:71], v[4:5], v[50:51], v[70:71] op_sel_hi:[0,1,1]
	v_pk_fma_f32 v[70:71], v[4:5], v[52:53], v[70:71] op_sel:[1,0,0]
	v_pk_mul_f32 v[76:77], v[62:63], v[66:67] op_sel_hi:[1,0]
	v_pk_mul_f32 v[92:93], v[64:65], v[66:67] op_sel_hi:[1,0]
	v_add_f32_dpp v74, v71, v70 row_mirror row_mask:0xf bank_mask:0xf bound_ctrl:1
	v_pk_fma_f32 v[76:77], v[2:3], v[54:55], v[76:77]
	v_pk_fma_f32 v[92:93], v[4:5], v[56:57], v[92:93]
	v_add_f32_dpp v74, v74, v74 row_half_mirror row_mask:0xf bank_mask:0xf bound_ctrl:1
	ds_read_b128 v[26:29], v94 offset:12800
	ds_read_b128 v[30:33], v94 offset:12816
	v_add_f32_dpp v74, v74, v74 quad_perm:[1,0,3,2] row_mask:0xf bank_mask:0xf bound_ctrl:1
	ds_read_b128 v[34:37], v94 offset:12832
	ds_read_b128 v[38:41], v94 offset:12848
	v_add_f32_dpp v74, v74, v74 quad_perm:[2,3,0,1] row_mask:0xf bank_mask:0xf bound_ctrl:1
	ds_read_b128 v[42:45], v94 offset:12864
	ds_write_b32 v97, v74 offset:1024
	ds_read2_b32 v[68:69], v95 offset0:160 offset1:176
	v_mov_b32_dpp v74, v74 row_mirror row_mask:0xf bank_mask:0xc
	v_pk_fma_f32 v[2:3], v[58:59], v[74:75], v[76:77] op_sel_hi:[1,0,1]
	v_pk_fma_f32 v[4:5], v[60:61], v[74:75], v[92:93] op_sel_hi:[1,0,1]
	s_waitcnt lgkmcnt(8)
	v_pk_mul_f32 v[70:71], v[2:3], v[6:7] op_sel_hi:[0,1]
	v_pk_fma_f32 v[70:71], v[2:3], v[8:9], v[70:71] op_sel:[1,0,0]
	v_pk_fma_f32 v[70:71], v[4:5], v[10:11], v[70:71] op_sel_hi:[0,1,1]
	v_pk_fma_f32 v[70:71], v[4:5], v[12:13], v[70:71] op_sel:[1,0,0]
	v_pk_mul_f32 v[76:77], v[22:23], v[66:67] op_sel:[0,1]
	v_pk_mul_f32 v[92:93], v[24:25], v[66:67] op_sel:[0,1]
	v_add_f32_dpp v74, v71, v70 row_mirror row_mask:0xf bank_mask:0xf bound_ctrl:1
	v_pk_fma_f32 v[76:77], v[2:3], v[14:15], v[76:77]
	v_pk_fma_f32 v[92:93], v[4:5], v[16:17], v[92:93]
	v_add_f32_dpp v74, v74, v74 row_half_mirror row_mask:0xf bank_mask:0xf bound_ctrl:1
	ds_read_b128 v[46:49], v94 offset:14080
	ds_read_b128 v[50:53], v94 offset:14096
	v_add_f32_dpp v74, v74, v74 quad_perm:[1,0,3,2] row_mask:0xf bank_mask:0xf bound_ctrl:1
	ds_read_b128 v[54:57], v94 offset:14112
	ds_read_b128 v[58:61], v94 offset:14128
	v_add_f32_dpp v74, v74, v74 quad_perm:[2,3,0,1] row_mask:0xf bank_mask:0xf bound_ctrl:1
	ds_read_b128 v[62:65], v94 offset:14144
	ds_write_b32 v97, v74 offset:1032
	v_mov_b32_dpp v74, v74 row_mirror row_mask:0xf bank_mask:0xc
	v_pk_fma_f32 v[2:3], v[18:19], v[74:75], v[76:77] op_sel_hi:[1,0,1]
	v_pk_fma_f32 v[4:5], v[20:21], v[74:75], v[92:93] op_sel_hi:[1,0,1]
	s_waitcnt lgkmcnt(6)
	v_pk_mul_f32 v[70:71], v[2:3], v[26:27] op_sel_hi:[0,1]
	v_pk_fma_f32 v[70:71], v[2:3], v[28:29], v[70:71] op_sel:[1,0,0]
	v_pk_fma_f32 v[70:71], v[4:5], v[30:31], v[70:71] op_sel_hi:[0,1,1]
	v_pk_fma_f32 v[70:71], v[4:5], v[32:33], v[70:71] op_sel:[1,0,0]
	v_pk_mul_f32 v[76:77], v[42:43], v[68:69] op_sel_hi:[1,0]
	v_pk_mul_f32 v[92:93], v[44:45], v[68:69] op_sel_hi:[1,0]
	v_add_f32_dpp v74, v71, v70 row_mirror row_mask:0xf bank_mask:0xf bound_ctrl:1
	v_pk_fma_f32 v[76:77], v[2:3], v[34:35], v[76:77]
	v_pk_fma_f32 v[92:93], v[4:5], v[36:37], v[92:93]
	v_add_f32_dpp v74, v74, v74 row_half_mirror row_mask:0xf bank_mask:0xf bound_ctrl:1
	ds_read_b128 v[6:9], v94 offset:15360
	ds_read_b128 v[10:13], v94 offset:15376
	v_add_f32_dpp v74, v74, v74 quad_perm:[1,0,3,2] row_mask:0xf bank_mask:0xf bound_ctrl:1
	ds_read_b128 v[14:17], v94 offset:15392
	ds_read_b128 v[18:21], v94 offset:15408
	v_add_f32_dpp v74, v74, v74 quad_perm:[2,3,0,1] row_mask:0xf bank_mask:0xf bound_ctrl:1
	ds_read_b128 v[22:25], v94 offset:15424
	ds_write_b32 v97, v74 offset:1280
	ds_read2_b32 v[66:67], v95 offset0:192 offset1:208
	v_mov_b32_dpp v74, v74 row_mirror row_mask:0xf bank_mask:0xc
	v_pk_fma_f32 v[2:3], v[38:39], v[74:75], v[76:77] op_sel_hi:[1,0,1]
	v_pk_fma_f32 v[4:5], v[40:41], v[74:75], v[92:93] op_sel_hi:[1,0,1]
	s_waitcnt lgkmcnt(8)
	v_pk_mul_f32 v[70:71], v[2:3], v[46:47] op_sel_hi:[0,1]
	v_pk_fma_f32 v[70:71], v[2:3], v[48:49], v[70:71] op_sel:[1,0,0]
	v_pk_fma_f32 v[70:71], v[4:5], v[50:51], v[70:71] op_sel_hi:[0,1,1]
	v_pk_fma_f32 v[70:71], v[4:5], v[52:53], v[70:71] op_sel:[1,0,0]
	v_pk_mul_f32 v[76:77], v[62:63], v[68:69] op_sel:[0,1]
	v_pk_mul_f32 v[92:93], v[64:65], v[68:69] op_sel:[0,1]
	v_add_f32_dpp v74, v71, v70 row_mirror row_mask:0xf bank_mask:0xf bound_ctrl:1
	v_pk_fma_f32 v[76:77], v[2:3], v[54:55], v[76:77]
	v_pk_fma_f32 v[92:93], v[4:5], v[56:57], v[92:93]
	v_add_f32_dpp v74, v74, v74 row_half_mirror row_mask:0xf bank_mask:0xf bound_ctrl:1
	ds_read_b128 v[26:29], v94 offset:16640
	ds_read_b128 v[30:33], v94 offset:16656
	v_add_f32_dpp v74, v74, v74 quad_perm:[1,0,3,2] row_mask:0xf bank_mask:0xf bound_ctrl:1
	ds_read_b128 v[34:37], v94 offset:16672
	ds_read_b128 v[38:41], v94 offset:16688
	v_add_f32_dpp v74, v74, v74 quad_perm:[2,3,0,1] row_mask:0xf bank_mask:0xf bound_ctrl:1
	ds_read_b128 v[42:45], v94 offset:16704
	ds_write_b32 v97, v74 offset:1288
	v_mov_b32_dpp v74, v74 row_mirror row_mask:0xf bank_mask:0xc
	v_pk_fma_f32 v[2:3], v[58:59], v[74:75], v[76:77] op_sel_hi:[1,0,1]
	v_pk_fma_f32 v[4:5], v[60:61], v[74:75], v[92:93] op_sel_hi:[1,0,1]
	s_waitcnt lgkmcnt(6)
	v_pk_mul_f32 v[70:71], v[2:3], v[6:7] op_sel_hi:[0,1]
	v_pk_fma_f32 v[70:71], v[2:3], v[8:9], v[70:71] op_sel:[1,0,0]
	v_pk_fma_f32 v[70:71], v[4:5], v[10:11], v[70:71] op_sel_hi:[0,1,1]
	v_pk_fma_f32 v[70:71], v[4:5], v[12:13], v[70:71] op_sel:[1,0,0]
	v_pk_mul_f32 v[76:77], v[22:23], v[66:67] op_sel_hi:[1,0]
	v_pk_mul_f32 v[92:93], v[24:25], v[66:67] op_sel_hi:[1,0]
	v_add_f32_dpp v74, v71, v70 row_mirror row_mask:0xf bank_mask:0xf bound_ctrl:1
	v_pk_fma_f32 v[76:77], v[2:3], v[14:15], v[76:77]
	v_pk_fma_f32 v[92:93], v[4:5], v[16:17], v[92:93]
	v_add_f32_dpp v74, v74, v74 row_half_mirror row_mask:0xf bank_mask:0xf bound_ctrl:1
	ds_read_b128 v[46:49], v94 offset:17920
	ds_read_b128 v[50:53], v94 offset:17936
	v_add_f32_dpp v74, v74, v74 quad_perm:[1,0,3,2] row_mask:0xf bank_mask:0xf bound_ctrl:1
	ds_read_b128 v[54:57], v94 offset:17952
	ds_read_b128 v[58:61], v94 offset:17968
	v_add_f32_dpp v74, v74, v74 quad_perm:[2,3,0,1] row_mask:0xf bank_mask:0xf bound_ctrl:1
	ds_read_b128 v[62:65], v94 offset:17984
	ds_write_b32 v97, v74 offset:1536
	ds_read2_b32 v[68:69], v95 offset0:224 offset1:240
	v_mov_b32_dpp v74, v74 row_mirror row_mask:0xf bank_mask:0xc
	v_pk_fma_f32 v[2:3], v[18:19], v[74:75], v[76:77] op_sel_hi:[1,0,1]
	v_pk_fma_f32 v[4:5], v[20:21], v[74:75], v[92:93] op_sel_hi:[1,0,1]
	s_waitcnt lgkmcnt(8)
	v_pk_mul_f32 v[70:71], v[2:3], v[26:27] op_sel_hi:[0,1]
	v_pk_fma_f32 v[70:71], v[2:3], v[28:29], v[70:71] op_sel:[1,0,0]
	v_pk_fma_f32 v[70:71], v[4:5], v[30:31], v[70:71] op_sel_hi:[0,1,1]
	v_pk_fma_f32 v[70:71], v[4:5], v[32:33], v[70:71] op_sel:[1,0,0]
	v_pk_mul_f32 v[76:77], v[42:43], v[66:67] op_sel:[0,1]
	v_pk_mul_f32 v[92:93], v[44:45], v[66:67] op_sel:[0,1]
	v_add_f32_dpp v74, v71, v70 row_mirror row_mask:0xf bank_mask:0xf bound_ctrl:1
	v_pk_fma_f32 v[76:77], v[2:3], v[34:35], v[76:77]
	v_pk_fma_f32 v[92:93], v[4:5], v[36:37], v[92:93]
	v_add_f32_dpp v74, v74, v74 row_half_mirror row_mask:0xf bank_mask:0xf bound_ctrl:1
	ds_read_b128 v[6:9], v94 offset:19200
	ds_read_b128 v[10:13], v94 offset:19216
	v_add_f32_dpp v74, v74, v74 quad_perm:[1,0,3,2] row_mask:0xf bank_mask:0xf bound_ctrl:1
	ds_read_b128 v[14:17], v94 offset:19232
	ds_read_b128 v[18:21], v94 offset:19248
	v_add_f32_dpp v74, v74, v74 quad_perm:[2,3,0,1] row_mask:0xf bank_mask:0xf bound_ctrl:1
	ds_read_b128 v[22:25], v94 offset:19264
	ds_write_b32 v97, v74 offset:1544
	v_mov_b32_dpp v74, v74 row_mirror row_mask:0xf bank_mask:0xc
	v_pk_fma_f32 v[2:3], v[38:39], v[74:75], v[76:77] op_sel_hi:[1,0,1]
	v_pk_fma_f32 v[4:5], v[40:41], v[74:75], v[92:93] op_sel_hi:[1,0,1]
	s_waitcnt lgkmcnt(6)
	v_pk_mul_f32 v[70:71], v[2:3], v[46:47] op_sel_hi:[0,1]
	v_pk_fma_f32 v[70:71], v[2:3], v[48:49], v[70:71] op_sel:[1,0,0]
	v_pk_fma_f32 v[70:71], v[4:5], v[50:51], v[70:71] op_sel_hi:[0,1,1]
	v_pk_fma_f32 v[70:71], v[4:5], v[52:53], v[70:71] op_sel:[1,0,0]
	v_pk_mul_f32 v[76:77], v[62:63], v[68:69] op_sel_hi:[1,0]
	v_pk_mul_f32 v[92:93], v[64:65], v[68:69] op_sel_hi:[1,0]
	v_add_f32_dpp v74, v71, v70 row_mirror row_mask:0xf bank_mask:0xf bound_ctrl:1
	v_pk_fma_f32 v[76:77], v[2:3], v[54:55], v[76:77]
	v_pk_fma_f32 v[92:93], v[4:5], v[56:57], v[92:93]
	v_add_f32_dpp v74, v74, v74 row_half_mirror row_mask:0xf bank_mask:0xf bound_ctrl:1
	ds_read_b128 v[26:29], v94 offset:20480
	ds_read_b128 v[30:33], v94 offset:20496
	v_add_f32_dpp v74, v74, v74 quad_perm:[1,0,3,2] row_mask:0xf bank_mask:0xf bound_ctrl:1
	ds_read_b128 v[34:37], v94 offset:20512
	ds_read_b128 v[38:41], v94 offset:20528
	v_add_f32_dpp v74, v74, v74 quad_perm:[2,3,0,1] row_mask:0xf bank_mask:0xf bound_ctrl:1
	ds_read_b128 v[42:45], v94 offset:20544
	ds_write_b32 v97, v74 offset:1792
	ds_read2_b32 v[66:67], v96 offset0:0 offset1:16
	v_mov_b32_dpp v74, v74 row_mirror row_mask:0xf bank_mask:0xc
	v_pk_fma_f32 v[2:3], v[58:59], v[74:75], v[76:77] op_sel_hi:[1,0,1]
	v_pk_fma_f32 v[4:5], v[60:61], v[74:75], v[92:93] op_sel_hi:[1,0,1]
	s_waitcnt lgkmcnt(8)
	v_pk_mul_f32 v[70:71], v[2:3], v[6:7] op_sel_hi:[0,1]
	v_pk_fma_f32 v[70:71], v[2:3], v[8:9], v[70:71] op_sel:[1,0,0]
	v_pk_fma_f32 v[70:71], v[4:5], v[10:11], v[70:71] op_sel_hi:[0,1,1]
	v_pk_fma_f32 v[70:71], v[4:5], v[12:13], v[70:71] op_sel:[1,0,0]
	v_pk_mul_f32 v[76:77], v[22:23], v[68:69] op_sel:[0,1]
	v_pk_mul_f32 v[92:93], v[24:25], v[68:69] op_sel:[0,1]
	v_add_f32_dpp v74, v71, v70 row_mirror row_mask:0xf bank_mask:0xf bound_ctrl:1
	v_pk_fma_f32 v[76:77], v[2:3], v[14:15], v[76:77]
	v_pk_fma_f32 v[92:93], v[4:5], v[16:17], v[92:93]
	v_add_f32_dpp v74, v74, v74 row_half_mirror row_mask:0xf bank_mask:0xf bound_ctrl:1
	ds_read_b128 v[46:49], v94 offset:21760
	ds_read_b128 v[50:53], v94 offset:21776
	v_add_f32_dpp v74, v74, v74 quad_perm:[1,0,3,2] row_mask:0xf bank_mask:0xf bound_ctrl:1
	ds_read_b128 v[54:57], v94 offset:21792
	ds_read_b128 v[58:61], v94 offset:21808
	v_add_f32_dpp v74, v74, v74 quad_perm:[2,3,0,1] row_mask:0xf bank_mask:0xf bound_ctrl:1
	ds_read_b128 v[62:65], v94 offset:21824
	ds_write_b32 v97, v74 offset:1800
	v_mov_b32_dpp v74, v74 row_mirror row_mask:0xf bank_mask:0xc
	v_pk_fma_f32 v[2:3], v[18:19], v[74:75], v[76:77] op_sel_hi:[1,0,1]
	v_pk_fma_f32 v[4:5], v[20:21], v[74:75], v[92:93] op_sel_hi:[1,0,1]
	s_waitcnt lgkmcnt(6)
	v_pk_mul_f32 v[70:71], v[2:3], v[26:27] op_sel_hi:[0,1]
	v_pk_fma_f32 v[70:71], v[2:3], v[28:29], v[70:71] op_sel:[1,0,0]
	v_pk_fma_f32 v[70:71], v[4:5], v[30:31], v[70:71] op_sel_hi:[0,1,1]
	v_pk_fma_f32 v[70:71], v[4:5], v[32:33], v[70:71] op_sel:[1,0,0]
	v_pk_mul_f32 v[76:77], v[42:43], v[66:67] op_sel_hi:[1,0]
	v_pk_mul_f32 v[92:93], v[44:45], v[66:67] op_sel_hi:[1,0]
	v_add_f32_dpp v74, v71, v70 row_mirror row_mask:0xf bank_mask:0xf bound_ctrl:1
	v_pk_fma_f32 v[76:77], v[2:3], v[34:35], v[76:77]
	v_pk_fma_f32 v[92:93], v[4:5], v[36:37], v[92:93]
	v_add_f32_dpp v74, v74, v74 row_half_mirror row_mask:0xf bank_mask:0xf bound_ctrl:1
	ds_read_b128 v[6:9], v94 offset:23040
	ds_read_b128 v[10:13], v94 offset:23056
	v_add_f32_dpp v74, v74, v74 quad_perm:[1,0,3,2] row_mask:0xf bank_mask:0xf bound_ctrl:1
	ds_read_b128 v[14:17], v94 offset:23072
	ds_read_b128 v[18:21], v94 offset:23088
	v_add_f32_dpp v74, v74, v74 quad_perm:[2,3,0,1] row_mask:0xf bank_mask:0xf bound_ctrl:1
	ds_read_b128 v[22:25], v94 offset:23104
	ds_write_b32 v97, v74 offset:2048
	ds_read2_b32 v[68:69], v96 offset0:32 offset1:48
	v_mov_b32_dpp v74, v74 row_mirror row_mask:0xf bank_mask:0xc
	v_pk_fma_f32 v[2:3], v[38:39], v[74:75], v[76:77] op_sel_hi:[1,0,1]
	v_pk_fma_f32 v[4:5], v[40:41], v[74:75], v[92:93] op_sel_hi:[1,0,1]
	s_waitcnt lgkmcnt(8)
	v_pk_mul_f32 v[70:71], v[2:3], v[46:47] op_sel_hi:[0,1]
	v_pk_fma_f32 v[70:71], v[2:3], v[48:49], v[70:71] op_sel:[1,0,0]
	v_pk_fma_f32 v[70:71], v[4:5], v[50:51], v[70:71] op_sel_hi:[0,1,1]
	v_pk_fma_f32 v[70:71], v[4:5], v[52:53], v[70:71] op_sel:[1,0,0]
	v_pk_mul_f32 v[76:77], v[62:63], v[66:67] op_sel:[0,1]
	v_pk_mul_f32 v[92:93], v[64:65], v[66:67] op_sel:[0,1]
	v_add_f32_dpp v74, v71, v70 row_mirror row_mask:0xf bank_mask:0xf bound_ctrl:1
	v_pk_fma_f32 v[76:77], v[2:3], v[54:55], v[76:77]
	v_pk_fma_f32 v[92:93], v[4:5], v[56:57], v[92:93]
	v_add_f32_dpp v74, v74, v74 row_half_mirror row_mask:0xf bank_mask:0xf bound_ctrl:1
	ds_read_b128 v[26:29], v94 offset:24320
	ds_read_b128 v[30:33], v94 offset:24336
	v_add_f32_dpp v74, v74, v74 quad_perm:[1,0,3,2] row_mask:0xf bank_mask:0xf bound_ctrl:1
	ds_read_b128 v[34:37], v94 offset:24352
	ds_read_b128 v[38:41], v94 offset:24368
	v_add_f32_dpp v74, v74, v74 quad_perm:[2,3,0,1] row_mask:0xf bank_mask:0xf bound_ctrl:1
	ds_read_b128 v[42:45], v94 offset:24384
	ds_write_b32 v97, v74 offset:2056
	v_mov_b32_dpp v74, v74 row_mirror row_mask:0xf bank_mask:0xc
	v_pk_fma_f32 v[2:3], v[58:59], v[74:75], v[76:77] op_sel_hi:[1,0,1]
	v_pk_fma_f32 v[4:5], v[60:61], v[74:75], v[92:93] op_sel_hi:[1,0,1]
	s_waitcnt lgkmcnt(6)
	v_pk_mul_f32 v[70:71], v[2:3], v[6:7] op_sel_hi:[0,1]
	v_pk_fma_f32 v[70:71], v[2:3], v[8:9], v[70:71] op_sel:[1,0,0]
	v_pk_fma_f32 v[70:71], v[4:5], v[10:11], v[70:71] op_sel_hi:[0,1,1]
	v_pk_fma_f32 v[70:71], v[4:5], v[12:13], v[70:71] op_sel:[1,0,0]
	v_pk_mul_f32 v[76:77], v[22:23], v[68:69] op_sel_hi:[1,0]
	v_pk_mul_f32 v[92:93], v[24:25], v[68:69] op_sel_hi:[1,0]
	v_add_f32_dpp v74, v71, v70 row_mirror row_mask:0xf bank_mask:0xf bound_ctrl:1
	v_pk_fma_f32 v[76:77], v[2:3], v[14:15], v[76:77]
	v_pk_fma_f32 v[92:93], v[4:5], v[16:17], v[92:93]
	v_add_f32_dpp v74, v74, v74 row_half_mirror row_mask:0xf bank_mask:0xf bound_ctrl:1
	ds_read_b128 v[46:49], v94 offset:25600
	ds_read_b128 v[50:53], v94 offset:25616
	v_add_f32_dpp v74, v74, v74 quad_perm:[1,0,3,2] row_mask:0xf bank_mask:0xf bound_ctrl:1
	ds_read_b128 v[54:57], v94 offset:25632
	ds_read_b128 v[58:61], v94 offset:25648
	v_add_f32_dpp v74, v74, v74 quad_perm:[2,3,0,1] row_mask:0xf bank_mask:0xf bound_ctrl:1
	ds_read_b128 v[62:65], v94 offset:25664
	ds_write_b32 v97, v74 offset:2304
	ds_read2_b32 v[66:67], v96 offset0:64 offset1:80
	v_mov_b32_dpp v74, v74 row_mirror row_mask:0xf bank_mask:0xc
	v_pk_fma_f32 v[2:3], v[18:19], v[74:75], v[76:77] op_sel_hi:[1,0,1]
	v_pk_fma_f32 v[4:5], v[20:21], v[74:75], v[92:93] op_sel_hi:[1,0,1]
	s_waitcnt lgkmcnt(8)
	v_pk_mul_f32 v[70:71], v[2:3], v[26:27] op_sel_hi:[0,1]
	v_pk_fma_f32 v[70:71], v[2:3], v[28:29], v[70:71] op_sel:[1,0,0]
	v_pk_fma_f32 v[70:71], v[4:5], v[30:31], v[70:71] op_sel_hi:[0,1,1]
	v_pk_fma_f32 v[70:71], v[4:5], v[32:33], v[70:71] op_sel:[1,0,0]
	v_pk_mul_f32 v[76:77], v[42:43], v[68:69] op_sel:[0,1]
	v_pk_mul_f32 v[92:93], v[44:45], v[68:69] op_sel:[0,1]
	v_add_f32_dpp v74, v71, v70 row_mirror row_mask:0xf bank_mask:0xf bound_ctrl:1
	v_pk_fma_f32 v[76:77], v[2:3], v[34:35], v[76:77]
	v_pk_fma_f32 v[92:93], v[4:5], v[36:37], v[92:93]
	v_add_f32_dpp v74, v74, v74 row_half_mirror row_mask:0xf bank_mask:0xf bound_ctrl:1
	ds_read_b128 v[6:9], v94 offset:26880
	ds_read_b128 v[10:13], v94 offset:26896
	v_add_f32_dpp v74, v74, v74 quad_perm:[1,0,3,2] row_mask:0xf bank_mask:0xf bound_ctrl:1
	ds_read_b128 v[14:17], v94 offset:26912
	ds_read_b128 v[18:21], v94 offset:26928
	v_add_f32_dpp v74, v74, v74 quad_perm:[2,3,0,1] row_mask:0xf bank_mask:0xf bound_ctrl:1
	ds_read_b128 v[22:25], v94 offset:26944
	ds_write_b32 v97, v74 offset:2312
	v_mov_b32_dpp v74, v74 row_mirror row_mask:0xf bank_mask:0xc
	v_pk_fma_f32 v[2:3], v[38:39], v[74:75], v[76:77] op_sel_hi:[1,0,1]
	v_pk_fma_f32 v[4:5], v[40:41], v[74:75], v[92:93] op_sel_hi:[1,0,1]
	s_waitcnt lgkmcnt(6)
	v_pk_mul_f32 v[70:71], v[2:3], v[46:47] op_sel_hi:[0,1]
	v_pk_fma_f32 v[70:71], v[2:3], v[48:49], v[70:71] op_sel:[1,0,0]
	v_pk_fma_f32 v[70:71], v[4:5], v[50:51], v[70:71] op_sel_hi:[0,1,1]
	v_pk_fma_f32 v[70:71], v[4:5], v[52:53], v[70:71] op_sel:[1,0,0]
	v_pk_mul_f32 v[76:77], v[62:63], v[66:67] op_sel_hi:[1,0]
	v_pk_mul_f32 v[92:93], v[64:65], v[66:67] op_sel_hi:[1,0]
	v_add_f32_dpp v74, v71, v70 row_mirror row_mask:0xf bank_mask:0xf bound_ctrl:1
	v_pk_fma_f32 v[76:77], v[2:3], v[54:55], v[76:77]
	v_pk_fma_f32 v[92:93], v[4:5], v[56:57], v[92:93]
	v_add_f32_dpp v74, v74, v74 row_half_mirror row_mask:0xf bank_mask:0xf bound_ctrl:1
	ds_read_b128 v[26:29], v94 offset:28160
	ds_read_b128 v[30:33], v94 offset:28176
	v_add_f32_dpp v74, v74, v74 quad_perm:[1,0,3,2] row_mask:0xf bank_mask:0xf bound_ctrl:1
	ds_read_b128 v[34:37], v94 offset:28192
	ds_read_b128 v[38:41], v94 offset:28208
	v_add_f32_dpp v74, v74, v74 quad_perm:[2,3,0,1] row_mask:0xf bank_mask:0xf bound_ctrl:1
	ds_read_b128 v[42:45], v94 offset:28224
	ds_write_b32 v97, v74 offset:2560
	ds_read2_b32 v[68:69], v96 offset0:96 offset1:112
	v_mov_b32_dpp v74, v74 row_mirror row_mask:0xf bank_mask:0xc
	v_pk_fma_f32 v[2:3], v[58:59], v[74:75], v[76:77] op_sel_hi:[1,0,1]
	v_pk_fma_f32 v[4:5], v[60:61], v[74:75], v[92:93] op_sel_hi:[1,0,1]
	s_waitcnt lgkmcnt(8)
	v_pk_mul_f32 v[70:71], v[2:3], v[6:7] op_sel_hi:[0,1]
	v_pk_fma_f32 v[70:71], v[2:3], v[8:9], v[70:71] op_sel:[1,0,0]
	v_pk_fma_f32 v[70:71], v[4:5], v[10:11], v[70:71] op_sel_hi:[0,1,1]
	v_pk_fma_f32 v[70:71], v[4:5], v[12:13], v[70:71] op_sel:[1,0,0]
	v_pk_mul_f32 v[76:77], v[22:23], v[66:67] op_sel:[0,1]
	v_pk_mul_f32 v[92:93], v[24:25], v[66:67] op_sel:[0,1]
	v_add_f32_dpp v74, v71, v70 row_mirror row_mask:0xf bank_mask:0xf bound_ctrl:1
	v_pk_fma_f32 v[76:77], v[2:3], v[14:15], v[76:77]
	v_pk_fma_f32 v[92:93], v[4:5], v[16:17], v[92:93]
	v_add_f32_dpp v74, v74, v74 row_half_mirror row_mask:0xf bank_mask:0xf bound_ctrl:1
	ds_read_b128 v[46:49], v94 offset:29440
	ds_read_b128 v[50:53], v94 offset:29456
	v_add_f32_dpp v74, v74, v74 quad_perm:[1,0,3,2] row_mask:0xf bank_mask:0xf bound_ctrl:1
	ds_read_b128 v[54:57], v94 offset:29472
	ds_read_b128 v[58:61], v94 offset:29488
	v_add_f32_dpp v74, v74, v74 quad_perm:[2,3,0,1] row_mask:0xf bank_mask:0xf bound_ctrl:1
	ds_read_b128 v[62:65], v94 offset:29504
	ds_write_b32 v97, v74 offset:2568
	v_mov_b32_dpp v74, v74 row_mirror row_mask:0xf bank_mask:0xc
	v_pk_fma_f32 v[2:3], v[18:19], v[74:75], v[76:77] op_sel_hi:[1,0,1]
	v_pk_fma_f32 v[4:5], v[20:21], v[74:75], v[92:93] op_sel_hi:[1,0,1]
	s_waitcnt lgkmcnt(6)
	v_pk_mul_f32 v[70:71], v[2:3], v[26:27] op_sel_hi:[0,1]
	v_pk_fma_f32 v[70:71], v[2:3], v[28:29], v[70:71] op_sel:[1,0,0]
	v_pk_fma_f32 v[70:71], v[4:5], v[30:31], v[70:71] op_sel_hi:[0,1,1]
	v_pk_fma_f32 v[70:71], v[4:5], v[32:33], v[70:71] op_sel:[1,0,0]
	v_pk_mul_f32 v[76:77], v[42:43], v[68:69] op_sel_hi:[1,0]
	v_pk_mul_f32 v[92:93], v[44:45], v[68:69] op_sel_hi:[1,0]
	v_add_f32_dpp v74, v71, v70 row_mirror row_mask:0xf bank_mask:0xf bound_ctrl:1
	v_pk_fma_f32 v[76:77], v[2:3], v[34:35], v[76:77]
	v_pk_fma_f32 v[92:93], v[4:5], v[36:37], v[92:93]
	v_add_f32_dpp v74, v74, v74 row_half_mirror row_mask:0xf bank_mask:0xf bound_ctrl:1
	ds_read_b128 v[6:9], v94 offset:30720
	ds_read_b128 v[10:13], v94 offset:30736
	v_add_f32_dpp v74, v74, v74 quad_perm:[1,0,3,2] row_mask:0xf bank_mask:0xf bound_ctrl:1
	ds_read_b128 v[14:17], v94 offset:30752
	ds_read_b128 v[18:21], v94 offset:30768
	v_add_f32_dpp v74, v74, v74 quad_perm:[2,3,0,1] row_mask:0xf bank_mask:0xf bound_ctrl:1
	ds_read_b128 v[22:25], v94 offset:30784
	ds_write_b32 v97, v74 offset:2816
	ds_read2_b32 v[66:67], v96 offset0:128 offset1:144
	v_mov_b32_dpp v74, v74 row_mirror row_mask:0xf bank_mask:0xc
	v_pk_fma_f32 v[2:3], v[38:39], v[74:75], v[76:77] op_sel_hi:[1,0,1]
	v_pk_fma_f32 v[4:5], v[40:41], v[74:75], v[92:93] op_sel_hi:[1,0,1]
	s_waitcnt lgkmcnt(8)
	v_pk_mul_f32 v[70:71], v[2:3], v[46:47] op_sel_hi:[0,1]
	v_pk_fma_f32 v[70:71], v[2:3], v[48:49], v[70:71] op_sel:[1,0,0]
	v_pk_fma_f32 v[70:71], v[4:5], v[50:51], v[70:71] op_sel_hi:[0,1,1]
	v_pk_fma_f32 v[70:71], v[4:5], v[52:53], v[70:71] op_sel:[1,0,0]
	v_pk_mul_f32 v[76:77], v[62:63], v[68:69] op_sel:[0,1]
	v_pk_mul_f32 v[92:93], v[64:65], v[68:69] op_sel:[0,1]
	v_add_f32_dpp v74, v71, v70 row_mirror row_mask:0xf bank_mask:0xf bound_ctrl:1
	v_pk_fma_f32 v[76:77], v[2:3], v[54:55], v[76:77]
	v_pk_fma_f32 v[92:93], v[4:5], v[56:57], v[92:93]
	v_add_f32_dpp v74, v74, v74 row_half_mirror row_mask:0xf bank_mask:0xf bound_ctrl:1
	ds_read_b128 v[26:29], v94 offset:32000
	ds_read_b128 v[30:33], v94 offset:32016
	v_add_f32_dpp v74, v74, v74 quad_perm:[1,0,3,2] row_mask:0xf bank_mask:0xf bound_ctrl:1
	ds_read_b128 v[34:37], v94 offset:32032
	ds_read_b128 v[38:41], v94 offset:32048
	v_add_f32_dpp v74, v74, v74 quad_perm:[2,3,0,1] row_mask:0xf bank_mask:0xf bound_ctrl:1
	ds_read_b128 v[42:45], v94 offset:32064
	ds_write_b32 v97, v74 offset:2824
	v_mov_b32_dpp v74, v74 row_mirror row_mask:0xf bank_mask:0xc
	v_pk_fma_f32 v[2:3], v[58:59], v[74:75], v[76:77] op_sel_hi:[1,0,1]
	v_pk_fma_f32 v[4:5], v[60:61], v[74:75], v[92:93] op_sel_hi:[1,0,1]
	s_waitcnt lgkmcnt(6)
	v_pk_mul_f32 v[70:71], v[2:3], v[6:7] op_sel_hi:[0,1]
	v_pk_fma_f32 v[70:71], v[2:3], v[8:9], v[70:71] op_sel:[1,0,0]
	v_pk_fma_f32 v[70:71], v[4:5], v[10:11], v[70:71] op_sel_hi:[0,1,1]
	v_pk_fma_f32 v[70:71], v[4:5], v[12:13], v[70:71] op_sel:[1,0,0]
	v_pk_mul_f32 v[76:77], v[22:23], v[66:67] op_sel_hi:[1,0]
	v_pk_mul_f32 v[92:93], v[24:25], v[66:67] op_sel_hi:[1,0]
	v_add_f32_dpp v74, v71, v70 row_mirror row_mask:0xf bank_mask:0xf bound_ctrl:1
	v_pk_fma_f32 v[76:77], v[2:3], v[14:15], v[76:77]
	v_pk_fma_f32 v[92:93], v[4:5], v[16:17], v[92:93]
	v_add_f32_dpp v74, v74, v74 row_half_mirror row_mask:0xf bank_mask:0xf bound_ctrl:1
	ds_read_b128 v[46:49], v94 offset:33280
	ds_read_b128 v[50:53], v94 offset:33296
	v_add_f32_dpp v74, v74, v74 quad_perm:[1,0,3,2] row_mask:0xf bank_mask:0xf bound_ctrl:1
	ds_read_b128 v[54:57], v94 offset:33312
	ds_read_b128 v[58:61], v94 offset:33328
	v_add_f32_dpp v74, v74, v74 quad_perm:[2,3,0,1] row_mask:0xf bank_mask:0xf bound_ctrl:1
	ds_read_b128 v[62:65], v94 offset:33344
	ds_write_b32 v97, v74 offset:3072
	ds_read2_b32 v[68:69], v96 offset0:160 offset1:176
	v_mov_b32_dpp v74, v74 row_mirror row_mask:0xf bank_mask:0xc
	v_pk_fma_f32 v[2:3], v[18:19], v[74:75], v[76:77] op_sel_hi:[1,0,1]
	v_pk_fma_f32 v[4:5], v[20:21], v[74:75], v[92:93] op_sel_hi:[1,0,1]
	s_waitcnt lgkmcnt(8)
	v_pk_mul_f32 v[70:71], v[2:3], v[26:27] op_sel_hi:[0,1]
	v_pk_fma_f32 v[70:71], v[2:3], v[28:29], v[70:71] op_sel:[1,0,0]
	v_pk_fma_f32 v[70:71], v[4:5], v[30:31], v[70:71] op_sel_hi:[0,1,1]
	v_pk_fma_f32 v[70:71], v[4:5], v[32:33], v[70:71] op_sel:[1,0,0]
	v_pk_mul_f32 v[76:77], v[42:43], v[66:67] op_sel:[0,1]
	v_pk_mul_f32 v[92:93], v[44:45], v[66:67] op_sel:[0,1]
	v_add_f32_dpp v74, v71, v70 row_mirror row_mask:0xf bank_mask:0xf bound_ctrl:1
	v_pk_fma_f32 v[76:77], v[2:3], v[34:35], v[76:77]
	v_pk_fma_f32 v[92:93], v[4:5], v[36:37], v[92:93]
	v_add_f32_dpp v74, v74, v74 row_half_mirror row_mask:0xf bank_mask:0xf bound_ctrl:1
	ds_read_b128 v[6:9], v94 offset:34560
	ds_read_b128 v[10:13], v94 offset:34576
	v_add_f32_dpp v74, v74, v74 quad_perm:[1,0,3,2] row_mask:0xf bank_mask:0xf bound_ctrl:1
	ds_read_b128 v[14:17], v94 offset:34592
	ds_read_b128 v[18:21], v94 offset:34608
	v_add_f32_dpp v74, v74, v74 quad_perm:[2,3,0,1] row_mask:0xf bank_mask:0xf bound_ctrl:1
	ds_read_b128 v[22:25], v94 offset:34624
	ds_write_b32 v97, v74 offset:3080
	v_mov_b32_dpp v74, v74 row_mirror row_mask:0xf bank_mask:0xc
	v_pk_fma_f32 v[2:3], v[38:39], v[74:75], v[76:77] op_sel_hi:[1,0,1]
	v_pk_fma_f32 v[4:5], v[40:41], v[74:75], v[92:93] op_sel_hi:[1,0,1]
	s_waitcnt lgkmcnt(6)
	v_pk_mul_f32 v[70:71], v[2:3], v[46:47] op_sel_hi:[0,1]
	v_pk_fma_f32 v[70:71], v[2:3], v[48:49], v[70:71] op_sel:[1,0,0]
	v_pk_fma_f32 v[70:71], v[4:5], v[50:51], v[70:71] op_sel_hi:[0,1,1]
	v_pk_fma_f32 v[70:71], v[4:5], v[52:53], v[70:71] op_sel:[1,0,0]
	v_pk_mul_f32 v[76:77], v[62:63], v[68:69] op_sel_hi:[1,0]
	v_pk_mul_f32 v[92:93], v[64:65], v[68:69] op_sel_hi:[1,0]
	v_add_f32_dpp v74, v71, v70 row_mirror row_mask:0xf bank_mask:0xf bound_ctrl:1
	v_pk_fma_f32 v[76:77], v[2:3], v[54:55], v[76:77]
	v_pk_fma_f32 v[92:93], v[4:5], v[56:57], v[92:93]
	v_add_f32_dpp v74, v74, v74 row_half_mirror row_mask:0xf bank_mask:0xf bound_ctrl:1
	ds_read_b128 v[26:29], v94 offset:35840
	ds_read_b128 v[30:33], v94 offset:35856
	v_add_f32_dpp v74, v74, v74 quad_perm:[1,0,3,2] row_mask:0xf bank_mask:0xf bound_ctrl:1
	ds_read_b128 v[34:37], v94 offset:35872
	ds_read_b128 v[38:41], v94 offset:35888
	v_add_f32_dpp v74, v74, v74 quad_perm:[2,3,0,1] row_mask:0xf bank_mask:0xf bound_ctrl:1
	ds_read_b128 v[42:45], v94 offset:35904
	ds_write_b32 v97, v74 offset:3328
	ds_read2_b32 v[66:67], v96 offset0:192 offset1:208
	v_mov_b32_dpp v74, v74 row_mirror row_mask:0xf bank_mask:0xc
	v_pk_fma_f32 v[2:3], v[58:59], v[74:75], v[76:77] op_sel_hi:[1,0,1]
	v_pk_fma_f32 v[4:5], v[60:61], v[74:75], v[92:93] op_sel_hi:[1,0,1]
	s_waitcnt lgkmcnt(8)
	v_pk_mul_f32 v[70:71], v[2:3], v[6:7] op_sel_hi:[0,1]
	v_pk_fma_f32 v[70:71], v[2:3], v[8:9], v[70:71] op_sel:[1,0,0]
	v_pk_fma_f32 v[70:71], v[4:5], v[10:11], v[70:71] op_sel_hi:[0,1,1]
	v_pk_fma_f32 v[70:71], v[4:5], v[12:13], v[70:71] op_sel:[1,0,0]
	v_pk_mul_f32 v[76:77], v[22:23], v[68:69] op_sel:[0,1]
	v_pk_mul_f32 v[92:93], v[24:25], v[68:69] op_sel:[0,1]
	v_add_f32_dpp v74, v71, v70 row_mirror row_mask:0xf bank_mask:0xf bound_ctrl:1
	v_pk_fma_f32 v[76:77], v[2:3], v[14:15], v[76:77]
	v_pk_fma_f32 v[92:93], v[4:5], v[16:17], v[92:93]
	v_add_f32_dpp v74, v74, v74 row_half_mirror row_mask:0xf bank_mask:0xf bound_ctrl:1
	ds_read_b128 v[46:49], v94 offset:37120
	ds_read_b128 v[50:53], v94 offset:37136
	v_add_f32_dpp v74, v74, v74 quad_perm:[1,0,3,2] row_mask:0xf bank_mask:0xf bound_ctrl:1
	ds_read_b128 v[54:57], v94 offset:37152
	ds_read_b128 v[58:61], v94 offset:37168
	v_add_f32_dpp v74, v74, v74 quad_perm:[2,3,0,1] row_mask:0xf bank_mask:0xf bound_ctrl:1
	ds_read_b128 v[62:65], v94 offset:37184
	ds_write_b32 v97, v74 offset:3336
	v_mov_b32_dpp v74, v74 row_mirror row_mask:0xf bank_mask:0xc
	v_pk_fma_f32 v[2:3], v[18:19], v[74:75], v[76:77] op_sel_hi:[1,0,1]
	v_pk_fma_f32 v[4:5], v[20:21], v[74:75], v[92:93] op_sel_hi:[1,0,1]
	s_waitcnt lgkmcnt(6)
	v_pk_mul_f32 v[70:71], v[2:3], v[26:27] op_sel_hi:[0,1]
	v_pk_fma_f32 v[70:71], v[2:3], v[28:29], v[70:71] op_sel:[1,0,0]
	v_pk_fma_f32 v[70:71], v[4:5], v[30:31], v[70:71] op_sel_hi:[0,1,1]
	v_pk_fma_f32 v[70:71], v[4:5], v[32:33], v[70:71] op_sel:[1,0,0]
	v_pk_mul_f32 v[76:77], v[42:43], v[66:67] op_sel_hi:[1,0]
	v_pk_mul_f32 v[92:93], v[44:45], v[66:67] op_sel_hi:[1,0]
	v_add_f32_dpp v74, v71, v70 row_mirror row_mask:0xf bank_mask:0xf bound_ctrl:1
	v_pk_fma_f32 v[76:77], v[2:3], v[34:35], v[76:77]
	v_pk_fma_f32 v[92:93], v[4:5], v[36:37], v[92:93]
	v_add_f32_dpp v74, v74, v74 row_half_mirror row_mask:0xf bank_mask:0xf bound_ctrl:1
	ds_read_b128 v[6:9], v94 offset:38400
	ds_read_b128 v[10:13], v94 offset:38416
	v_add_f32_dpp v74, v74, v74 quad_perm:[1,0,3,2] row_mask:0xf bank_mask:0xf bound_ctrl:1
	ds_read_b128 v[14:17], v94 offset:38432
	ds_read_b128 v[18:21], v94 offset:38448
	v_add_f32_dpp v74, v74, v74 quad_perm:[2,3,0,1] row_mask:0xf bank_mask:0xf bound_ctrl:1
	ds_read_b128 v[22:25], v94 offset:38464
	ds_write_b32 v97, v74 offset:3584
	ds_read2_b32 v[68:69], v96 offset0:224 offset1:240
	v_mov_b32_dpp v74, v74 row_mirror row_mask:0xf bank_mask:0xc
	v_pk_fma_f32 v[2:3], v[38:39], v[74:75], v[76:77] op_sel_hi:[1,0,1]
	v_pk_fma_f32 v[4:5], v[40:41], v[74:75], v[92:93] op_sel_hi:[1,0,1]
	s_waitcnt lgkmcnt(8)
	v_pk_mul_f32 v[70:71], v[2:3], v[46:47] op_sel_hi:[0,1]
	v_pk_fma_f32 v[70:71], v[2:3], v[48:49], v[70:71] op_sel:[1,0,0]
	v_pk_fma_f32 v[70:71], v[4:5], v[50:51], v[70:71] op_sel_hi:[0,1,1]
	v_pk_fma_f32 v[70:71], v[4:5], v[52:53], v[70:71] op_sel:[1,0,0]
	v_pk_mul_f32 v[76:77], v[62:63], v[66:67] op_sel:[0,1]
	v_pk_mul_f32 v[92:93], v[64:65], v[66:67] op_sel:[0,1]
	v_add_f32_dpp v74, v71, v70 row_mirror row_mask:0xf bank_mask:0xf bound_ctrl:1
	v_pk_fma_f32 v[76:77], v[2:3], v[54:55], v[76:77]
	v_pk_fma_f32 v[92:93], v[4:5], v[56:57], v[92:93]
	v_add_f32_dpp v74, v74, v74 row_half_mirror row_mask:0xf bank_mask:0xf bound_ctrl:1
	ds_read_b128 v[26:29], v94 offset:39680
	ds_read_b128 v[30:33], v94 offset:39696
	v_add_f32_dpp v74, v74, v74 quad_perm:[1,0,3,2] row_mask:0xf bank_mask:0xf bound_ctrl:1
	ds_read_b128 v[34:37], v94 offset:39712
	ds_read_b128 v[38:41], v94 offset:39728
	v_add_f32_dpp v74, v74, v74 quad_perm:[2,3,0,1] row_mask:0xf bank_mask:0xf bound_ctrl:1
	ds_read_b128 v[42:45], v94 offset:39744
	ds_write_b32 v97, v74 offset:3592
	v_mov_b32_dpp v74, v74 row_mirror row_mask:0xf bank_mask:0xc
	v_pk_fma_f32 v[2:3], v[58:59], v[74:75], v[76:77] op_sel_hi:[1,0,1]
	v_pk_fma_f32 v[4:5], v[60:61], v[74:75], v[92:93] op_sel_hi:[1,0,1]
	s_waitcnt lgkmcnt(6)
	v_pk_mul_f32 v[70:71], v[2:3], v[6:7] op_sel_hi:[0,1]
	v_pk_fma_f32 v[70:71], v[2:3], v[8:9], v[70:71] op_sel:[1,0,0]
	v_pk_fma_f32 v[70:71], v[4:5], v[10:11], v[70:71] op_sel_hi:[0,1,1]
	v_pk_fma_f32 v[70:71], v[4:5], v[12:13], v[70:71] op_sel:[1,0,0]
	v_pk_mul_f32 v[76:77], v[22:23], v[68:69] op_sel_hi:[1,0]
	v_pk_mul_f32 v[92:93], v[24:25], v[68:69] op_sel_hi:[1,0]
	v_add_f32_dpp v74, v71, v70 row_mirror row_mask:0xf bank_mask:0xf bound_ctrl:1
	v_pk_fma_f32 v[76:77], v[2:3], v[14:15], v[76:77]
	v_pk_fma_f32 v[92:93], v[4:5], v[16:17], v[92:93]
	v_add_f32_dpp v74, v74, v74 row_half_mirror row_mask:0xf bank_mask:0xf bound_ctrl:1
	s_nop 1
	v_add_f32_dpp v74, v74, v74 quad_perm:[1,0,3,2] row_mask:0xf bank_mask:0xf bound_ctrl:1
	s_nop 1
	v_add_f32_dpp v74, v74, v74 quad_perm:[2,3,0,1] row_mask:0xf bank_mask:0xf bound_ctrl:1
	s_nop 0
	ds_write_b32 v97, v74 offset:3840
	v_mov_b32_dpp v74, v74 row_mirror row_mask:0xf bank_mask:0xc
	v_pk_fma_f32 v[2:3], v[18:19], v[74:75], v[76:77] op_sel_hi:[1,0,1]
	v_pk_fma_f32 v[4:5], v[20:21], v[74:75], v[92:93] op_sel_hi:[1,0,1]
	s_waitcnt lgkmcnt(2)
	v_pk_mul_f32 v[70:71], v[2:3], v[26:27] op_sel_hi:[0,1]
	v_pk_fma_f32 v[70:71], v[2:3], v[28:29], v[70:71] op_sel:[1,0,0]
	v_pk_fma_f32 v[70:71], v[4:5], v[30:31], v[70:71] op_sel_hi:[0,1,1]
	v_pk_fma_f32 v[70:71], v[4:5], v[32:33], v[70:71] op_sel:[1,0,0]
	v_pk_mul_f32 v[76:77], v[42:43], v[68:69] op_sel:[0,1]
	v_pk_mul_f32 v[92:93], v[44:45], v[68:69] op_sel:[0,1]
	v_add_f32_dpp v74, v71, v70 row_mirror row_mask:0xf bank_mask:0xf bound_ctrl:1
	v_pk_fma_f32 v[76:77], v[2:3], v[34:35], v[76:77]
	v_pk_fma_f32 v[92:93], v[4:5], v[36:37], v[92:93]
	v_add_f32_dpp v74, v74, v74 row_half_mirror row_mask:0xf bank_mask:0xf bound_ctrl:1
	s_nop 1
	v_add_f32_dpp v74, v74, v74 quad_perm:[1,0,3,2] row_mask:0xf bank_mask:0xf bound_ctrl:1
	s_nop 1
	v_add_f32_dpp v74, v74, v74 quad_perm:[2,3,0,1] row_mask:0xf bank_mask:0xf bound_ctrl:1
	s_nop 0
	ds_write_b32 v97, v74 offset:3848
	v_mov_b32_dpp v74, v74 row_mirror row_mask:0xf bank_mask:0xc
	v_pk_fma_f32 v[2:3], v[38:39], v[74:75], v[76:77] op_sel_hi:[1,0,1]
	v_pk_fma_f32 v[4:5], v[40:41], v[74:75], v[92:93] op_sel_hi:[1,0,1]
	s_add_i32 s33, s33, 1
	s_cmpk_lg_i32 s33, 0x80
	s_waitcnt lgkmcnt(0)
	s_barrier
	s_cbranch_scc1 .Lscan_chunk
	s_setprio 0
